# pool phase: next token row prefetched one iteration ahead; plus attention scalar-base stage DMAs (on top of v165)
# speedup vs baseline: 1.0007x; 1.0007x over previous
.LBB0_346:
	s_or_b64 exec, exec, s[2:3]
	s_lshl_b32 s2, s48, 2
	v_subrev_u32_e32 v2, s2, v4
	v_add3_u32 v4, 0, 64, v2
	v_lshl_add_u64 v[22:23], v[8:9], 0, v[0:1]
	v_lshl_add_u64 v[24:25], v[12:13], 0, v[0:1]
	v_add_u32_e32 v35, 1, v3
	s_mov_b64 s[2:3], 0
	s_mov_b32 s96, 0x12a00000
	s_mov_b32 s97, 0
	v_lshl_add_u64 v[46:47], v[22:23], 0, s[96:97]
	global_load_dwordx4 v[46:49], v[46:47], off
	s_mov_b32 s96, 0x12a01000
	s_branch .LBB0_348

.LBB0_348:
	v_lshl_add_u64 v[26:27], v[22:23], 0, s[2:3]
	v_min_u32_e32 v36, v35, v29
	v_cvt_f32_ubyte0_e32 v37, v36
	v_div_scale_f32 v38, s[36:37], v37, v37, 1.0
	v_rcp_f32_e32 v39, v38
	v_div_scale_f32 v40, vcc, 1.0, v37, 1.0
	ds_read_b32 v36, v4
	v_fma_f32 v41, -v38, v39, 1.0
	v_fmac_f32_e32 v39, v41, v39
	v_mul_f32_e32 v41, v40, v39
	v_fma_f32 v42, -v38, v41, v40
	v_fmac_f32_e32 v41, v42, v39
	v_fma_f32 v38, -v38, v41, v40
	v_div_fmas_f32 v38, v38, v39, v41
	v_div_fixup_f32 v37, v38, v37, 1.0
	v_cmp_ge_u32_e32 vcc, v35, v29
	s_waitcnt vmcnt(0)
	v_lshlrev_b32_e32 v38, 16, v46
	v_and_b32_e32 v39, 0xffff0000, v46
	v_lshlrev_b32_e32 v0, 16, v47
	v_and_b32_e32 v1, 0xffff0000, v47
	v_lshlrev_b32_e32 v40, 16, v48
	v_and_b32_e32 v41, 0xffff0000, v48
	v_lshlrev_b32_e32 v2, 16, v49
	v_and_b32_e32 v3, 0xffff0000, v49
	v_lshl_add_u64 v[46:47], v[26:27], 0, s[96:97]
	global_load_dwordx4 v[46:49], v[46:47], off
	s_waitcnt lgkmcnt(0)
	v_pk_mul_f32 v[42:43], v[36:37], v[38:39] op_sel_hi:[0,1]
	v_pk_fma_f32 v[14:15], v[36:37], v[38:39], v[14:15] op_sel_hi:[0,1,1]
	v_pk_mul_f32 v[38:39], v[36:37], v[0:1] op_sel_hi:[0,1]
	v_pk_fma_f32 v[18:19], v[36:37], v[0:1], v[18:19] op_sel_hi:[0,1,1]
	v_pk_mul_f32 v[0:1], v[36:37], v[40:41] op_sel_hi:[0,1]
	v_pk_fma_f32 v[20:21], v[36:37], v[40:41], v[20:21] op_sel_hi:[0,1,1]
	v_pk_mul_f32 v[40:41], v[36:37], v[2:3] op_sel_hi:[0,1]
	v_pk_fma_f32 v[16:17], v[36:37], v[2:3], v[16:17] op_sel_hi:[0,1,1]
	v_fma_f32 v2, v37, v14, -v42
	v_fma_f32 v3, v37, v15, -v43
	v_fma_f32 v36, v37, v18, -v38
	v_fma_f32 v38, v37, v19, -v39
	v_fma_f32 v39, v37, v20, -v0
	v_fma_f32 v42, v37, v21, -v1
	v_fma_f32 v40, v37, v16, -v40
	v_fma_f32 v37, v37, v17, -v41
	v_cvt_pk_bf16_f32 v0, v2, v3
	v_cvt_pk_bf16_f32 v1, v36, v38
	v_cvt_pk_bf16_f32 v2, v39, v42
	v_cvt_pk_bf16_f32 v3, v40, v37
	s_and_saveexec_b64 s[36:37], vcc
	s_cbranch_execz .LBB0_347
	v_lshl_add_u64 v[36:37], v[24:25], 0, s[2:3]
	global_load_dwordx4 v[36:39], v[36:37], off
	v_add_u32_e32 v40, v4, v32
	ds_read_b32 v40, v40 offset:4
	s_waitcnt vmcnt(0)
	v_lshlrev_b32_e32 v42, 16, v36
	v_and_b32_e32 v43, 0xffff0000, v36
	v_lshlrev_b32_e32 v36, 16, v37
	v_and_b32_e32 v37, 0xffff0000, v37
	v_lshlrev_b32_e32 v44, 16, v38
	v_and_b32_e32 v45, 0xffff0000, v38
	v_lshlrev_b32_e32 v38, 16, v39
	v_and_b32_e32 v39, 0xffff0000, v39
	s_waitcnt lgkmcnt(0)
	v_pk_fma_f32 v[14:15], v[40:41], v[42:43], v[14:15] op_sel_hi:[0,1,1] neg_lo:[1,0,0] neg_hi:[1,0,0]
	v_pk_fma_f32 v[18:19], v[40:41], v[36:37], v[18:19] op_sel_hi:[0,1,1] neg_lo:[1,0,0] neg_hi:[1,0,0]
	v_pk_fma_f32 v[20:21], v[40:41], v[44:45], v[20:21] op_sel_hi:[0,1,1] neg_lo:[1,0,0] neg_hi:[1,0,0]
	v_pk_fma_f32 v[16:17], v[40:41], v[38:39], v[16:17] op_sel_hi:[0,1,1] neg_lo:[1,0,0] neg_hi:[1,0,0]
	s_branch .LBB0_347
